# snsa score loop: relative-position bias table staged in LDS (was a global gather + drain per key); dead SGPR tuple reloads removed
# speedup vs baseline: 1.0419x; 1.0048x over previous
; #define LAS __attribute__((address_space(3)))
; DI void snsa_unit(const Args& a, LAS unsigned char* lds, int s, int g) {
;     ...
;     const float* rbias = INF(a, I_RB); const int* pt = (const int*)a.in[I_PT] + s * NPAGES;
;     const bf16_t* kcb = (const bf16_t*)(ws + WS_KC) + ((size_t)AROWS_P + (size_t)(s * 2 + g) * 1024) * 64; const bf16_t* vcb = kcb + (size_t)AROWS * 64;
;     __syncthreads();
;     if (tid < 256) Q[tid] = bf2f(((const bf16_t*)(ws + WS_QA))[row * 512 + g * 256 + tid]);
;     __syncthreads();
;     f32x4 q4[4];
; #pragma unroll
;     for (int hq = 0; hq < 4; ++hq) q4[hq] = *(const LAS f32x4*)(Q + hq * 64 + 4 * c16);
;     const int myh = 2 * (c16 & 1) + ((c16 >> 1) & 1);
; #pragma unroll 1
;     for (int br = 0; br < 3; ++br) {
;         const int nkeys = br == 0 ? 1023 : (br == 1 ? 1024 : 512);
; #pragma unroll 1
;         for (int k0 = ksl; k0 < nkeys; k0 += 256) {
;             f32x4 x[8]; int dist[8]; bool valid[8];
; #pragma unroll
;             for (int u = 0; u < 8; ++u) { const int kk = k0 + 32 * u; const int kc = kk < nkeys ? kk : k0;
;                 if (br == 0) { const u32x2 w = *(const u32x2*)(kcb + (size_t)kc * 64 + 4 * c16); x[u] = (f32x4){bf2f(w.x & 0xffffu), bf2f(w.x >> 16), bf2f(w.y & 0xffffu), bf2f(w.y >> 16)}; dist[u] = 16353 - 16 * kc; valid[u] = true; }
;                 else { const float* kp; const float* vp; snsa_key(a, br, kc, s, g, SEL, pt, kp, vp, dist[u], valid[u]); x[u] = *(const f32x4*)(kp + 4 * c16); if (c16 == 0 && kk < nkeys) VP[kk] = (unsigned long long)(uintptr_t)vp; } }
.LBB0_1458:
	s_or_b64 exec, exec, s[6:7]
	s_lshl_b32 s6, s4, 7
	s_ashr_i32 s7, s6, 31
	v_readlane_b32 s8, v253, 36
	s_lshl_b64 s[6:7], s[6:7], 2
	v_readlane_b32 s10, v253, 38
	v_readlane_b32 s11, v253, 39
	s_add_u32 s74, s10, s6
	s_addc_u32 s75, s11, s7
	v_readlane_b32 s36, v253, 40
	v_readlane_b32 s37, v253, 41
	v_cmp_gt_u32_e32 vcc, 0x100, v72
	s_and_saveexec_b64 s[100:101], vcc
	v_lshlrev_b32_e32 v2, 2, v72
	s_nop 1
	global_load_dword v1, v2, s[36:37]
	s_waitcnt vmcnt(0)
	ds_write_b32 v2, v1 offset:63296
	s_or_b64 exec, exec, s[100:101]
	v_cmp_gt_u32_e32 vcc, 0x80, v72
	s_and_saveexec_b64 s[100:101], vcc
	v_lshlrev_b32_e32 v2, 2, v72
	global_load_dword v1, v2, s[74:75]
	s_waitcnt vmcnt(0)
	ds_write_b32 v2, v1 offset:62784
	s_or_b64 exec, exec, s[100:101]
	s_ashr_i32 s1, s0, 31
	s_lshl_b64 s[0:1], s[0:1], 17
	v_readlane_b32 s36, v254, 49
	v_readlane_b32 s37, v254, 50
	s_add_u32 s10, s36, s0
	s_addc_u32 s11, s37, s1
	s_cmp_lt_i32 s2, 4
	s_cselect_b64 s[6:7], -1, 0
	v_and_b32_e32 v1, 15, v72
	v_writelane_b32 v254, s6, 27
	s_movk_i32 s3, 0x101
	v_lshlrev_b32_e32 v6, 4, v1
	v_writelane_b32 v254, s7, 28
	v_cmp_gt_i32_e64 s[6:7], s3, v72
	v_readlane_b32 s12, v253, 40
	v_readlane_b32 s13, v253, 41
	v_add_u32_e32 v2, 0, v6
	v_writelane_b32 v254, s6, 29
	v_readlane_b32 s14, v253, 42
	v_readlane_b32 s15, v253, 43
	s_waitcnt lgkmcnt(0)
	s_barrier
	ds_read_b128 v[22:25], v2 offset:24576
	ds_read_b128 v[26:29], v2 offset:24832
	ds_read_b128 v[30:33], v2 offset:25088
	ds_read_b128 v[34:37], v2 offset:25344
	v_and_b32_e32 v2, 1, v72
	v_bfrev_b32_e32 v3, v72
	v_writelane_b32 v254, s7, 30
	v_cmp_eq_u32_e64 s[12:13], 0, v1
	v_lshlrev_b32_e32 v70, 3, v1
	v_lshlrev_b32_e32 v8, 2, v72
	v_lshlrev_b32_e32 v76, 2, v1
	v_cmp_ne_u32_e64 s[6:7], 0, v1
	v_writelane_b32 v254, s12, 11
	v_lshl_add_u64 v[78:79], s[10:11], 0, v[70:71]
	v_cmp_eq_u32_e64 s[10:11], 0, v2
	v_and_b32_e32 v2, 2, v72
	v_cmp_gt_u32_e64 s[14:15], 4, v1
	v_lshrrev_b32_e32 v1, 18, v3
	v_writelane_b32 v254, s13, 12
	v_cmp_eq_u32_e64 s[12:13], 0, v2
	v_and_b32_e32 v2, 0x3000, v1
	v_add_u32_e32 v1, -1, v8
	v_cmp_lt_i32_e32 vcc, 0, v72
	s_lshl_b32 s3, s24, 2
	v_writelane_b32 v252, s3, 7
	v_cndmask_b32_e32 v9, 0, v1, vcc
	v_or_b32_e32 v1, 3, v8
	s_lshl_b32 s34, s2, 12
	s_mov_b64 s[2:3], 0x840000
	v_min_i32_e32 v100, 0x3fe, v1
	v_lshl_add_u64 v[80:81], v[78:79], 0, s[2:3]
	v_cmp_le_i32_e64 s[2:3], v9, v100
	v_readlane_b32 s18, v253, 46
	v_readlane_b32 s19, v253, 47
	v_writelane_b32 v254, s2, 35
	v_cmp_eq_u32_e32 vcc, 0, v72
	v_readlane_b32 s9, v253, 37
	v_writelane_b32 v254, s3, 36
	s_movk_i32 s2, 0xfe
	v_cmp_lt_i32_e64 s[18:19], s2, v72
	s_or_b64 s[2:3], vcc, s[18:19]
	s_ashr_i32 s5, s4, 31
	v_writelane_b32 v252, s2, 8
	v_readlane_b32 s16, v253, 44
	v_readlane_b32 s17, v253, 45
	v_readlane_b32 s20, v253, 48
	v_readlane_b32 s21, v253, 49
	v_readlane_b32 s22, v253, 50
	v_readlane_b32 s23, v253, 51
	s_lshl_b64 s[8:9], s[4:5], 19
	s_lshl_b32 s76, s24, 6
	s_lshl_b64 s[4:5], s[4:5], 11
	v_writelane_b32 v252, s3, 9
	v_readlane_b32 s2, v254, 53
	s_mov_b32 s35, s24
	s_add_u32 s38, s2, s8
	v_readlane_b32 s2, v254, 54
	v_readlane_b32 s16, v253, 20
	s_addc_u32 s77, s2, s9
	v_readlane_b32 s26, v253, 30
	v_readlane_b32 s27, v253, 31
	s_add_u32 s96, s26, s8
	s_addc_u32 s97, s27, s9
	v_readlane_b32 s2, v254, 55
	s_add_u32 s2, s2, s4
	v_readlane_b32 s3, v254, 56
	s_addc_u32 s3, s3, s5
	s_lshl_b32 s4, s35, 8
	s_add_u32 s2, s2, s4
	v_ashrrev_i32_e32 v74, 4, v72
	s_addc_u32 s3, s3, 0
	s_add_u32 s62, s2, 0x400
	v_lshlrev_b32_e32 v10, 2, v74
	s_addc_u32 s63, s3, 0
	v_add3_u32 v105, v2, v10, 0
	v_and_b32_e32 v2, -16, v72
	v_ashrrev_i32_e32 v75, 31, v74
	s_add_u32 s64, s2, 0x600
	v_alignbit_b32 v104, s35, v3, 30
	s_movk_i32 s2, 0x100
	v_sub_u32_e32 v107, 0x3fe1, v2
	v_lshlrev_b64 v[2:3], 7, v[74:75]
	s_addc_u32 s65, s3, 0
	v_cmp_lt_i32_e64 s[4:5], s2, v72
	s_add_i32 s2, 0, 0x4000
	v_lshl_add_u64 v[2:3], s[0:1], 0, v[2:3]
	v_readlane_b32 s0, v254, 61
	v_writelane_b32 v252, s35, 10
	s_add_u32 s0, s0, s8
	v_readlane_b32 s1, v254, 62
	v_and_b32_e32 v73, 63, v72
	v_writelane_b32 v252, s4, 11
	v_lshlrev_b64 v[4:5], 10, v[74:75]
	s_addc_u32 s1, s1, s9
	v_writelane_b32 v252, s5, 12
	v_lshl_add_u64 v[84:85], s[0:1], 0, v[4:5]
	v_lshlrev_b32_e32 v108, 2, v73
	s_add_i32 s0, s34, 0
	v_writelane_b32 v252, s0, 13
	v_add_u32_e32 v109, s0, v108
	v_readlane_b32 s0, v254, 63
	v_or_b32_e32 v2, v2, v70
	v_readlane_b32 s1, v252, 0
	v_lshl_add_u64 v[82:83], s[36:37], 0, v[2:3]
	v_lshl_add_u32 v7, v74, 10, 0
	v_lshl_add_u64 v[86:87], s[0:1], 0, v[2:3]
	v_lshlrev_b32_e32 v2, 2, v9
	v_readlane_b32 s0, v252, 1
	s_mov_b32 s3, s38
	v_add_u32_e32 v99, 0, v8
	v_add_u32_e32 v113, s0, v2
	v_readlane_b32 s0, v252, 2
	v_and_b32_e32 v101, 63, v74
	v_bitop3_b32 v102, v72, 63, v72 bitop3:0x3f
	v_add_u32_e32 v114, s0, v2
	s_add_i32 s0, 0, 0x3000
	v_add_u32_e32 v115, s0, v2
	v_readlane_b32 s0, v252, 3
	v_or_b32_e32 v103, 64, v73
	v_mov_b32_e32 v1, v72
	v_add_u32_e32 v116, s0, v8
	s_mov_b64 s[0:1], 0
	v_writelane_b32 v254, s0, 33
	v_lshl_add_u32 v106, v74, 3, s2
	s_mov_b32 s8, 0
	v_writelane_b32 v254, s1, 34
	s_mov_b64 s[0:1], 0
	v_writelane_b32 v252, s0, 14
	v_sub_u32_e32 v75, 0x1ff, v74
	v_add_u32_e32 v110, 0, v10
	v_writelane_b32 v252, s1, 15
	s_mov_b64 s[0:1], 0
	v_writelane_b32 v252, s0, 16
	v_add_u32_e32 v111, -1, v9
	v_add_u32_e32 v112, 0, v2
	v_writelane_b32 v252, s1, 17
	s_mov_b64 s[0:1], 0
	v_writelane_b32 v252, s0, 18
	s_mov_b64 s[40:41], 0
	v_add_u32_e32 v117, v7, v6
	v_writelane_b32 v252, s1, 19
	s_mov_b64 s[0:1], 0
	v_writelane_b32 v252, s0, 20
	v_writelane_b32 v254, s3, 31
	v_readlane_b32 s17, v253, 21
	v_writelane_b32 v252, s1, 21
	s_mov_b64 s[0:1], 0
	v_writelane_b32 v252, s0, 22
	v_readlane_b32 s18, v253, 22
	v_readlane_b32 s19, v253, 23
	v_writelane_b32 v252, s1, 23
	s_mov_b64 s[0:1], 0
	v_writelane_b32 v252, s0, 24
	v_readlane_b32 s20, v253, 24
	v_readlane_b32 s21, v253, 25
	v_readlane_b32 s22, v253, 26
	v_readlane_b32 s23, v253, 27
	v_readlane_b32 s24, v253, 28
	v_readlane_b32 s25, v253, 29
	v_readlane_b32 s28, v253, 32
	v_readlane_b32 s29, v253, 33
	v_readlane_b32 s30, v253, 34
	v_readlane_b32 s31, v253, 35
	v_writelane_b32 v252, s1, 25
	s_branch .LBB0_1460

; DI void snsa_unit(const Args& a, LAS unsigned char* lds, int s, int g) {
;     ...
;                 float ka = o1 ? p2 : p0, kb2 = o1 ? p3 : p1; const float sa = o1 ? p0 : p2, sb = o1 ? p1 : p3;
;                 ka += __shfl_xor(sa, 1); kb2 += __shfl_xor(sb, 1);
;                 float e = o2 ? kb2 : ka; const float f = o2 ? ka : kb2;
;                 e += __shfl_xor(f, 2); e += __shfl_xor(e, 4); e += __shfl_xor(e, 8);
;                 if (c16 < 4 && kk < nkeys) SC[myh * 1024 + kk] = valid[u] ? e + rbias[rel_bucket(dist[u]) * 8 + g * 4 + myh] * LOG2E : -INFINITY; }
.LBB0_1462:
	s_or_b64 exec, exec, s[82:83]
	v_lshl_or_b32 v70, v16, 3, v104
	v_lshlrev_b32_e32 v70, 2, v70
	ds_read_b32 v70, v70 offset:63296
	s_waitcnt lgkmcnt(1)
	v_add_f32_e32 v6, v14, v15
	s_waitcnt lgkmcnt(0)
	v_fmac_f32_e32 v6, 0x3fb8aa3b, v70

; #define LAS __attribute__((address_space(3)))
; DI void snsa_key(const Args& a, int br, int kk, int s, int g, const LAS int* SEL, const int* pt, const float*& kp, const float*& vp, int& dist, bool& valid) {
;     valid = true;
;     if (br == 1) { const int pos = SEL[kk >> 6] * 64 + (kk & 63); dist = PAST - pos; valid = pos <= PAST;
;         if (pos < PAST) { const float* base = INF(a, I_CKV) + ((size_t)pt[pos >> 7] * PAGE + (pos & 127)) * 512; kp = base + 256 + g * 64; vp = base + 384 + g * 64; }
;         else { const float* base = a.out + O_KVS + (size_t)s * 512; kp = base + 256 + g * 64; vp = base + 384 + g * 64; } }
; DI void snsa_unit(const Args& a, LAS unsigned char* lds, int s, int g) {
;     ...
;             for (int u = 0; u < 8; ++u) { const int kk = k0 + 32 * u; const int kc = kk < nkeys ? kk : k0;
;                 if (br == 0) { const u32x2 w = *(const u32x2*)(kcb + (size_t)kc * 64 + 4 * c16); x[u] = (f32x4){bf2f(w.x & 0xffffu), bf2f(w.x >> 16), bf2f(w.y & 0xffffu), bf2f(w.y >> 16)}; dist[u] = 16353 - 16 * kc; valid[u] = true; }
;                 else { const float* kp; const float* vp; snsa_key(a, br, kc, s, g, SEL, pt, kp, vp, dist[u], valid[u]); x[u] = *(const f32x4*)(kp + 4 * c16); if (c16 == 0 && kk < nkeys) VP[kk] = (unsigned long long)(uintptr_t)vp; } }
.LBB0_1468:
	s_andn2_b64 vcc, exec, s[4:5]
	s_cbranch_vccnz .LBB0_1472
	v_ashrrev_i32_e32 v6, 6, v123
	v_lshl_add_u32 v6, v6, 2, 0
	ds_read_b32 v11, v6 offset:62720
	v_mov_b64_e32 v[6:7], s[64:65]
	v_mov_b64_e32 v[8:9], s[62:63]
	s_waitcnt lgkmcnt(0)
	v_lshl_or_b32 v10, v11, 6, v101
	v_cmp_gt_i32_e64 s[20:21], s81, v10
	v_cmp_gt_i32_e32 vcc, s80, v10
	s_and_saveexec_b64 s[4:5], vcc
	s_cbranch_execz .LBB0_1471
	v_ashrrev_i32_e32 v6, 1, v11
	v_lshlrev_b32_e32 v6, 2, v6
	ds_read_b32 v6, v6 offset:62784
	v_lshlrev_b32_e32 v7, 11, v10
	v_and_b32_e32 v70, 0x3f800, v7
	v_readlane_b32 s44, v253, 28
	v_readlane_b32 s45, v253, 29
	s_lshl_b32 s72, s76, 2
	s_mov_b64 s[24:25], 0x400
	s_waitcnt lgkmcnt(0)
	v_ashrrev_i32_e32 v7, 31, v6
	v_lshlrev_b64 v[6:7], 18, v[6:7]
	v_lshl_add_u64 v[6:7], s[44:45], 0, v[6:7]
	v_lshl_add_u64 v[6:7], v[6:7], 0, v[70:71]
	v_lshl_add_u64 v[6:7], v[6:7], 0, s[72:73]
	v_lshl_add_u64 v[8:9], v[6:7], 0, s[24:25]
	v_lshl_add_u64 v[6:7], v[6:7], 0, s[84:85]

; #define LAS __attribute__((address_space(3)))
; DI void snsa_key(const Args& a, int br, int kk, int s, int g, const LAS int* SEL, const int* pt, const float*& kp, const float*& vp, int& dist, bool& valid) {
;     valid = true;
;     if (br == 1) { const int pos = SEL[kk >> 6] * 64 + (kk & 63); dist = PAST - pos; valid = pos <= PAST;
;         if (pos < PAST) { const float* base = INF(a, I_CKV) + ((size_t)pt[pos >> 7] * PAGE + (pos & 127)) * 512; kp = base + 256 + g * 64; vp = base + 384 + g * 64; }
;         else { const float* base = a.out + O_KVS + (size_t)s * 512; kp = base + 256 + g * 64; vp = base + 384 + g * 64; } }
; DI void snsa_unit(const Args& a, LAS unsigned char* lds, int s, int g) {
;     ...
;             for (int u = 0; u < 8; ++u) { const int kk = k0 + 32 * u; const int kc = kk < nkeys ? kk : k0;
;                 if (br == 0) { const u32x2 w = *(const u32x2*)(kcb + (size_t)kc * 64 + 4 * c16); x[u] = (f32x4){bf2f(w.x & 0xffffu), bf2f(w.x >> 16), bf2f(w.y & 0xffffu), bf2f(w.y >> 16)}; dist[u] = 16353 - 16 * kc; valid[u] = true; }
;                 else { const float* kp; const float* vp; snsa_key(a, br, kc, s, g, SEL, pt, kp, vp, dist[u], valid[u]); x[u] = *(const f32x4*)(kp + 4 * c16); if (c16 == 0 && kk < nkeys) VP[kk] = (unsigned long long)(uintptr_t)vp; } }
.LBB0_1480:
	s_andn2_b64 vcc, exec, s[4:5]
	s_cbranch_vccnz .LBB0_1484
	v_ashrrev_i32_e32 v6, 6, v46
	v_lshl_add_u32 v6, v6, 2, 0
	ds_read_b32 v7, v6 offset:62720
	v_and_b32_e32 v6, 63, v46
	v_mov_b64_e32 v[48:49], s[64:65]
	v_mov_b64_e32 v[42:43], s[62:63]
	s_waitcnt lgkmcnt(0)
	v_lshl_or_b32 v6, v7, 6, v6
	v_cmp_gt_i32_e64 s[58:59], s81, v6
	v_cmp_gt_i32_e32 vcc, s80, v6
	s_and_saveexec_b64 s[4:5], vcc
	s_cbranch_execz .LBB0_1483
	v_ashrrev_i32_e32 v8, 1, v7
	v_lshlrev_b32_e32 v8, 2, v8
	ds_read_b32 v8, v8 offset:62784
	v_lshlrev_b32_e32 v7, 11, v6
	v_readlane_b32 s44, v253, 28
	v_readlane_b32 s45, v253, 29
	v_and_b32_e32 v70, 0x3f800, v7
	s_lshl_b32 s72, s76, 2
	s_mov_b64 s[36:37], 0x400
	s_waitcnt lgkmcnt(0)
	v_ashrrev_i32_e32 v9, 31, v8
	v_lshlrev_b64 v[8:9], 18, v[8:9]
	v_lshl_add_u64 v[8:9], s[44:45], 0, v[8:9]
	v_lshl_add_u64 v[8:9], v[8:9], 0, v[70:71]
	v_lshl_add_u64 v[8:9], v[8:9], 0, s[72:73]
	v_lshl_add_u64 v[42:43], v[8:9], 0, s[36:37]
	v_lshl_add_u64 v[48:49], v[8:9], 0, s[84:85]

; #define LAS __attribute__((address_space(3)))
; DI void snsa_key(const Args& a, int br, int kk, int s, int g, const LAS int* SEL, const int* pt, const float*& kp, const float*& vp, int& dist, bool& valid) {
;     valid = true;
;     if (br == 1) { const int pos = SEL[kk >> 6] * 64 + (kk & 63); dist = PAST - pos; valid = pos <= PAST;
;         if (pos < PAST) { const float* base = INF(a, I_CKV) + ((size_t)pt[pos >> 7] * PAGE + (pos & 127)) * 512; kp = base + 256 + g * 64; vp = base + 384 + g * 64; }
;         else { const float* base = a.out + O_KVS + (size_t)s * 512; kp = base + 256 + g * 64; vp = base + 384 + g * 64; } }
; DI void snsa_unit(const Args& a, LAS unsigned char* lds, int s, int g) {
;     ...
;             for (int u = 0; u < 8; ++u) { const int kk = k0 + 32 * u; const int kc = kk < nkeys ? kk : k0;
;                 if (br == 0) { const u32x2 w = *(const u32x2*)(kcb + (size_t)kc * 64 + 4 * c16); x[u] = (f32x4){bf2f(w.x & 0xffffu), bf2f(w.x >> 16), bf2f(w.y & 0xffffu), bf2f(w.y >> 16)}; dist[u] = 16353 - 16 * kc; valid[u] = true; }
;                 else { const float* kp; const float* vp; snsa_key(a, br, kc, s, g, SEL, pt, kp, vp, dist[u], valid[u]); x[u] = *(const f32x4*)(kp + 4 * c16); if (c16 == 0 && kk < nkeys) VP[kk] = (unsigned long long)(uintptr_t)vp; } }
.LBB0_1492:
	s_andn2_b64 vcc, exec, s[66:67]
	s_cbranch_vccnz .LBB0_1496
	v_ashrrev_i32_e32 v14, 6, v50
	v_lshl_add_u32 v14, v14, 2, 0
	s_waitcnt lgkmcnt(0)
	ds_read_b32 v15, v14 offset:62720
	v_and_b32_e32 v14, 63, v50
	v_mov_b64_e32 v[52:53], s[64:65]
	v_mov_b64_e32 v[46:47], s[62:63]
	s_waitcnt lgkmcnt(0)
	v_lshl_or_b32 v14, v15, 6, v14
	v_cmp_gt_i32_e64 s[4:5], s81, v14
	v_cmp_gt_i32_e32 vcc, s80, v14
	s_and_saveexec_b64 s[66:67], vcc
	s_cbranch_execz .LBB0_1495
	v_ashrrev_i32_e32 v16, 1, v15
	v_lshlrev_b32_e32 v16, 2, v16
	ds_read_b32 v16, v16 offset:62784
	v_lshlrev_b32_e32 v15, 11, v14
	v_readlane_b32 s44, v253, 28
	v_readlane_b32 s45, v253, 29
	v_and_b32_e32 v70, 0x3f800, v15
	s_lshl_b32 s72, s76, 2
	s_mov_b64 s[36:37], 0x400
	s_waitcnt lgkmcnt(0)
	v_ashrrev_i32_e32 v17, 31, v16
	v_lshlrev_b64 v[16:17], 18, v[16:17]
	v_lshl_add_u64 v[16:17], s[44:45], 0, v[16:17]
	v_lshl_add_u64 v[16:17], v[16:17], 0, v[70:71]
	v_lshl_add_u64 v[16:17], v[16:17], 0, s[72:73]
	v_lshl_add_u64 v[46:47], v[16:17], 0, s[36:37]
	v_lshl_add_u64 v[52:53], v[16:17], 0, s[84:85]

; #define LAS __attribute__((address_space(3)))
; DI void snsa_key(const Args& a, int br, int kk, int s, int g, const LAS int* SEL, const int* pt, const float*& kp, const float*& vp, int& dist, bool& valid) {
;     valid = true;
;     if (br == 1) { const int pos = SEL[kk >> 6] * 64 + (kk & 63); dist = PAST - pos; valid = pos <= PAST;
;         if (pos < PAST) { const float* base = INF(a, I_CKV) + ((size_t)pt[pos >> 7] * PAGE + (pos & 127)) * 512; kp = base + 256 + g * 64; vp = base + 384 + g * 64; }
;         else { const float* base = a.out + O_KVS + (size_t)s * 512; kp = base + 256 + g * 64; vp = base + 384 + g * 64; } }
; DI void snsa_unit(const Args& a, LAS unsigned char* lds, int s, int g) {
;     ...
;             for (int u = 0; u < 8; ++u) { const int kk = k0 + 32 * u; const int kc = kk < nkeys ? kk : k0;
;                 if (br == 0) { const u32x2 w = *(const u32x2*)(kcb + (size_t)kc * 64 + 4 * c16); x[u] = (f32x4){bf2f(w.x & 0xffffu), bf2f(w.x >> 16), bf2f(w.y & 0xffffu), bf2f(w.y >> 16)}; dist[u] = 16353 - 16 * kc; valid[u] = true; }
;                 else { const float* kp; const float* vp; snsa_key(a, br, kc, s, g, SEL, pt, kp, vp, dist[u], valid[u]); x[u] = *(const f32x4*)(kp + 4 * c16); if (c16 == 0 && kk < nkeys) VP[kk] = (unsigned long long)(uintptr_t)vp; } }
.LBB0_1504:
	s_andn2_b64 vcc, exec, s[68:69]
	s_cbranch_vccnz .LBB0_1508
	v_ashrrev_i32_e32 v6, 6, v54
	v_lshl_add_u32 v6, v6, 2, 0
	ds_read_b32 v7, v6 offset:62720
	v_and_b32_e32 v6, 63, v54
	v_mov_b64_e32 v[56:57], s[64:65]
	v_mov_b64_e32 v[50:51], s[62:63]
	s_waitcnt lgkmcnt(0)
	v_lshl_or_b32 v6, v7, 6, v6
	v_cmp_gt_i32_e64 s[66:67], s81, v6
	v_cmp_gt_i32_e32 vcc, s80, v6
	s_and_saveexec_b64 s[68:69], vcc
	s_cbranch_execz .LBB0_1507
	v_ashrrev_i32_e32 v8, 1, v7
	v_lshlrev_b32_e32 v8, 2, v8
	ds_read_b32 v8, v8 offset:62784
	v_lshlrev_b32_e32 v7, 11, v6
	v_readlane_b32 s44, v253, 28
	v_readlane_b32 s45, v253, 29
	v_and_b32_e32 v70, 0x3f800, v7
	s_lshl_b32 s72, s76, 2
	s_mov_b64 s[36:37], 0x400
	s_waitcnt lgkmcnt(0)
	v_ashrrev_i32_e32 v9, 31, v8
	v_lshlrev_b64 v[8:9], 18, v[8:9]
	v_lshl_add_u64 v[8:9], s[44:45], 0, v[8:9]
	v_lshl_add_u64 v[8:9], v[8:9], 0, v[70:71]
	v_lshl_add_u64 v[8:9], v[8:9], 0, s[72:73]
	v_lshl_add_u64 v[50:51], v[8:9], 0, s[36:37]
	v_lshl_add_u64 v[56:57], v[8:9], 0, s[84:85]

; #define LAS __attribute__((address_space(3)))
; DI void snsa_key(const Args& a, int br, int kk, int s, int g, const LAS int* SEL, const int* pt, const float*& kp, const float*& vp, int& dist, bool& valid) {
;     valid = true;
;     if (br == 1) { const int pos = SEL[kk >> 6] * 64 + (kk & 63); dist = PAST - pos; valid = pos <= PAST;
;         if (pos < PAST) { const float* base = INF(a, I_CKV) + ((size_t)pt[pos >> 7] * PAGE + (pos & 127)) * 512; kp = base + 256 + g * 64; vp = base + 384 + g * 64; }
;         else { const float* base = a.out + O_KVS + (size_t)s * 512; kp = base + 256 + g * 64; vp = base + 384 + g * 64; } }
; DI void snsa_unit(const Args& a, LAS unsigned char* lds, int s, int g) {
;     ...
;             for (int u = 0; u < 8; ++u) { const int kk = k0 + 32 * u; const int kc = kk < nkeys ? kk : k0;
;                 if (br == 0) { const u32x2 w = *(const u32x2*)(kcb + (size_t)kc * 64 + 4 * c16); x[u] = (f32x4){bf2f(w.x & 0xffffu), bf2f(w.x >> 16), bf2f(w.y & 0xffffu), bf2f(w.y >> 16)}; dist[u] = 16353 - 16 * kc; valid[u] = true; }
;                 else { const float* kp; const float* vp; snsa_key(a, br, kc, s, g, SEL, pt, kp, vp, dist[u], valid[u]); x[u] = *(const f32x4*)(kp + 4 * c16); if (c16 == 0 && kk < nkeys) VP[kk] = (unsigned long long)(uintptr_t)vp; } }
.LBB0_1516:
	s_andn2_b64 vcc, exec, s[70:71]
	s_cbranch_vccnz .LBB0_1520
	v_ashrrev_i32_e32 v14, 6, v58
	v_lshl_add_u32 v14, v14, 2, 0
	s_waitcnt lgkmcnt(0)
	ds_read_b32 v15, v14 offset:62720
	v_and_b32_e32 v14, 63, v58
	v_mov_b64_e32 v[60:61], s[64:65]
	v_mov_b64_e32 v[54:55], s[62:63]
	s_waitcnt lgkmcnt(0)
	v_lshl_or_b32 v14, v15, 6, v14
	v_cmp_gt_i32_e64 s[68:69], s81, v14
	v_cmp_gt_i32_e32 vcc, s80, v14
	s_and_saveexec_b64 s[70:71], vcc
	s_cbranch_execz .LBB0_1519
	v_ashrrev_i32_e32 v16, 1, v15
	v_lshlrev_b32_e32 v16, 2, v16
	ds_read_b32 v16, v16 offset:62784
	v_lshlrev_b32_e32 v15, 11, v14
	v_readlane_b32 s44, v253, 28
	v_readlane_b32 s45, v253, 29
	v_and_b32_e32 v70, 0x3f800, v15
	s_lshl_b32 s72, s76, 2
	s_mov_b64 s[36:37], 0x400
	s_waitcnt lgkmcnt(0)
	v_ashrrev_i32_e32 v17, 31, v16
	v_lshlrev_b64 v[16:17], 18, v[16:17]
	v_lshl_add_u64 v[16:17], s[44:45], 0, v[16:17]
	v_lshl_add_u64 v[16:17], v[16:17], 0, v[70:71]
	v_lshl_add_u64 v[16:17], v[16:17], 0, s[72:73]
	v_lshl_add_u64 v[54:55], v[16:17], 0, s[36:37]
	v_lshl_add_u64 v[60:61], v[16:17], 0, s[84:85]

; #define LAS __attribute__((address_space(3)))
; DI void snsa_key(const Args& a, int br, int kk, int s, int g, const LAS int* SEL, const int* pt, const float*& kp, const float*& vp, int& dist, bool& valid) {
;     valid = true;
;     if (br == 1) { const int pos = SEL[kk >> 6] * 64 + (kk & 63); dist = PAST - pos; valid = pos <= PAST;
;         if (pos < PAST) { const float* base = INF(a, I_CKV) + ((size_t)pt[pos >> 7] * PAGE + (pos & 127)) * 512; kp = base + 256 + g * 64; vp = base + 384 + g * 64; }
;         else { const float* base = a.out + O_KVS + (size_t)s * 512; kp = base + 256 + g * 64; vp = base + 384 + g * 64; } }
; DI void snsa_unit(const Args& a, LAS unsigned char* lds, int s, int g) {
;     ...
;             for (int u = 0; u < 8; ++u) { const int kk = k0 + 32 * u; const int kc = kk < nkeys ? kk : k0;
;                 if (br == 0) { const u32x2 w = *(const u32x2*)(kcb + (size_t)kc * 64 + 4 * c16); x[u] = (f32x4){bf2f(w.x & 0xffffu), bf2f(w.x >> 16), bf2f(w.y & 0xffffu), bf2f(w.y >> 16)}; dist[u] = 16353 - 16 * kc; valid[u] = true; }
;                 else { const float* kp; const float* vp; snsa_key(a, br, kc, s, g, SEL, pt, kp, vp, dist[u], valid[u]); x[u] = *(const f32x4*)(kp + 4 * c16); if (c16 == 0 && kk < nkeys) VP[kk] = (unsigned long long)(uintptr_t)vp; } }
.LBB0_1528:
	s_andn2_b64 vcc, exec, s[78:79]
	s_cbranch_vccnz .LBB0_1532
	v_ashrrev_i32_e32 v6, 6, v62
	v_lshl_add_u32 v6, v6, 2, 0
	ds_read_b32 v7, v6 offset:62720
	v_and_b32_e32 v6, 63, v62
	v_mov_b64_e32 v[64:65], s[64:65]
	v_mov_b64_e32 v[58:59], s[62:63]
	s_waitcnt lgkmcnt(0)
	v_lshl_or_b32 v6, v7, 6, v6
	v_cmp_gt_i32_e64 s[70:71], s81, v6
	v_cmp_gt_i32_e32 vcc, s80, v6
	s_and_saveexec_b64 s[78:79], vcc
	s_cbranch_execz .LBB0_1531
	v_ashrrev_i32_e32 v8, 1, v7
	v_lshlrev_b32_e32 v8, 2, v8
	ds_read_b32 v8, v8 offset:62784
	v_lshlrev_b32_e32 v7, 11, v6
	v_readlane_b32 s44, v253, 28
	v_readlane_b32 s45, v253, 29
	v_and_b32_e32 v70, 0x3f800, v7
	s_lshl_b32 s72, s76, 2
	s_mov_b64 s[36:37], 0x400
	s_waitcnt lgkmcnt(0)
	v_ashrrev_i32_e32 v9, 31, v8
	v_lshlrev_b64 v[8:9], 18, v[8:9]
	v_lshl_add_u64 v[8:9], s[44:45], 0, v[8:9]
	v_lshl_add_u64 v[8:9], v[8:9], 0, v[70:71]
	v_lshl_add_u64 v[8:9], v[8:9], 0, s[72:73]
	v_lshl_add_u64 v[58:59], v[8:9], 0, s[36:37]
	v_lshl_add_u64 v[64:65], v[8:9], 0, s[84:85]

; #define LAS __attribute__((address_space(3)))
; DI void snsa_key(const Args& a, int br, int kk, int s, int g, const LAS int* SEL, const int* pt, const float*& kp, const float*& vp, int& dist, bool& valid) {
;     valid = true;
;     if (br == 1) { const int pos = SEL[kk >> 6] * 64 + (kk & 63); dist = PAST - pos; valid = pos <= PAST;
;         if (pos < PAST) { const float* base = INF(a, I_CKV) + ((size_t)pt[pos >> 7] * PAGE + (pos & 127)) * 512; kp = base + 256 + g * 64; vp = base + 384 + g * 64; }
;         else { const float* base = a.out + O_KVS + (size_t)s * 512; kp = base + 256 + g * 64; vp = base + 384 + g * 64; } }
; DI void snsa_unit(const Args& a, LAS unsigned char* lds, int s, int g) {
;     ...
;             for (int u = 0; u < 8; ++u) { const int kk = k0 + 32 * u; const int kc = kk < nkeys ? kk : k0;
;                 if (br == 0) { const u32x2 w = *(const u32x2*)(kcb + (size_t)kc * 64 + 4 * c16); x[u] = (f32x4){bf2f(w.x & 0xffffu), bf2f(w.x >> 16), bf2f(w.y & 0xffffu), bf2f(w.y >> 16)}; dist[u] = 16353 - 16 * kc; valid[u] = true; }
;                 else { const float* kp; const float* vp; snsa_key(a, br, kc, s, g, SEL, pt, kp, vp, dist[u], valid[u]); x[u] = *(const f32x4*)(kp + 4 * c16); if (c16 == 0 && kk < nkeys) VP[kk] = (unsigned long long)(uintptr_t)vp; } }
.LBB0_1540:
	s_andn2_b64 vcc, exec, s[82:83]
	s_cbranch_vccnz .LBB0_1544
	v_ashrrev_i32_e32 v14, 6, v66
	v_lshl_add_u32 v14, v14, 2, 0
	s_waitcnt lgkmcnt(0)
	ds_read_b32 v15, v14 offset:62720
	v_and_b32_e32 v14, 63, v66
	v_mov_b64_e32 v[68:69], s[64:65]
	v_mov_b64_e32 v[62:63], s[62:63]
	s_waitcnt lgkmcnt(0)
	v_lshl_or_b32 v14, v15, 6, v14
	v_cmp_gt_i32_e64 s[78:79], s81, v14
	v_cmp_gt_i32_e32 vcc, s80, v14
	s_and_saveexec_b64 s[82:83], vcc
	s_cbranch_execz .LBB0_1543
	v_ashrrev_i32_e32 v16, 1, v15
	v_lshlrev_b32_e32 v16, 2, v16
	ds_read_b32 v16, v16 offset:62784
	v_lshlrev_b32_e32 v15, 11, v14
	v_readlane_b32 s44, v253, 28
	v_readlane_b32 s45, v253, 29
	v_and_b32_e32 v70, 0x3f800, v15
	s_lshl_b32 s72, s76, 2
	s_mov_b64 s[36:37], 0x400
	s_waitcnt lgkmcnt(0)
	v_ashrrev_i32_e32 v17, 31, v16
	v_lshlrev_b64 v[16:17], 18, v[16:17]
	v_lshl_add_u64 v[16:17], s[44:45], 0, v[16:17]
	v_lshl_add_u64 v[16:17], v[16:17], 0, v[70:71]
	v_lshl_add_u64 v[16:17], v[16:17], 0, s[72:73]
	v_lshl_add_u64 v[62:63], v[16:17], 0, s[36:37]
	v_lshl_add_u64 v[68:69], v[16:17], 0, s[84:85]

; DI void snsa_unit(const Args& a, LAS unsigned char* lds, int s, int g) {
;     ...
;                 float ka = o1 ? p2 : p0, kb2 = o1 ? p3 : p1; const float sa = o1 ? p0 : p2, sb = o1 ? p1 : p3;
;                 ka += __shfl_xor(sa, 1); kb2 += __shfl_xor(sb, 1);
;                 float e = o2 ? kb2 : ka; const float f = o2 ? ka : kb2;
;                 e += __shfl_xor(f, 2); e += __shfl_xor(e, 4); e += __shfl_xor(e, 8);
;                 if (c16 < 4 && kk < nkeys) SC[myh * 1024 + kk] = valid[u] ? e + rbias[rel_bucket(dist[u]) * 8 + g * 4 + myh] * LOG2E : -INFINITY; }
.LBB0_1565:
	s_andn2_saveexec_b64 s[82:83], s[82:83]
	v_max_i32_e32 v17, 0, v6
	s_or_b64 exec, exec, s[82:83]
	v_lshl_or_b32 v70, v17, 3, v104
	v_lshlrev_b32_e32 v70, 2, v70
	ds_read_b32 v70, v70 offset:63296
	s_waitcnt lgkmcnt(1)
	v_add_f32_e32 v16, v14, v15
	s_waitcnt lgkmcnt(0)
	v_fmac_f32_e32 v16, 0x3fb8aa3b, v70

; DI void snsa_unit(const Args& a, LAS unsigned char* lds, int s, int g) {
;     ...
;                 float ka = o1 ? p2 : p0, kb2 = o1 ? p3 : p1; const float sa = o1 ? p0 : p2, sb = o1 ? p1 : p3;
;                 ka += __shfl_xor(sa, 1); kb2 += __shfl_xor(sb, 1);
;                 float e = o2 ? kb2 : ka; const float f = o2 ? ka : kb2;
;                 e += __shfl_xor(f, 2); e += __shfl_xor(e, 4); e += __shfl_xor(e, 8);
;                 if (c16 < 4 && kk < nkeys) SC[myh * 1024 + kk] = valid[u] ? e + rbias[rel_bucket(dist[u]) * 8 + g * 4 + myh] * LOG2E : -INFINITY; }
.LBB0_1573:
	s_andn2_saveexec_b64 s[82:83], s[82:83]
	v_max_i32_e32 v16, 0, v7
	s_or_b64 exec, exec, s[82:83]
	v_lshl_or_b32 v70, v16, 3, v104
	v_lshlrev_b32_e32 v70, 2, v70
	ds_read_b32 v70, v70 offset:63296
	s_waitcnt lgkmcnt(1)
	v_add_f32_e32 v15, v6, v14
	s_waitcnt lgkmcnt(0)
	v_fmac_f32_e32 v15, 0x3fb8aa3b, v70

; DI void snsa_unit(const Args& a, LAS unsigned char* lds, int s, int g) {
;     ...
;                 float ka = o1 ? p2 : p0, kb2 = o1 ? p3 : p1; const float sa = o1 ? p0 : p2, sb = o1 ? p1 : p3;
;                 ka += __shfl_xor(sa, 1); kb2 += __shfl_xor(sb, 1);
;                 float e = o2 ? kb2 : ka; const float f = o2 ? ka : kb2;
;                 e += __shfl_xor(f, 2); e += __shfl_xor(e, 4); e += __shfl_xor(e, 8);
;                 if (c16 < 4 && kk < nkeys) SC[myh * 1024 + kk] = valid[u] ? e + rbias[rel_bucket(dist[u]) * 8 + g * 4 + myh] * LOG2E : -INFINITY; }
.LBB0_1581:
	s_andn2_saveexec_b64 s[82:83], s[82:83]
	v_max_i32_e32 v15, 0, v8
	s_or_b64 exec, exec, s[82:83]
	v_lshl_or_b32 v70, v15, 3, v104
	v_lshlrev_b32_e32 v70, 2, v70
	ds_read_b32 v70, v70 offset:63296
	s_waitcnt lgkmcnt(1)
	v_add_f32_e32 v14, v6, v7
	s_waitcnt lgkmcnt(0)
	v_fmac_f32_e32 v14, 0x3fb8aa3b, v70

; DI void snsa_unit(const Args& a, LAS unsigned char* lds, int s, int g) {
;     ...
;                 float ka = o1 ? p2 : p0, kb2 = o1 ? p3 : p1; const float sa = o1 ? p0 : p2, sb = o1 ? p1 : p3;
;                 ka += __shfl_xor(sa, 1); kb2 += __shfl_xor(sb, 1);
;                 float e = o2 ? kb2 : ka; const float f = o2 ? ka : kb2;
;                 e += __shfl_xor(f, 2); e += __shfl_xor(e, 4); e += __shfl_xor(e, 8);
;                 if (c16 < 4 && kk < nkeys) SC[myh * 1024 + kk] = valid[u] ? e + rbias[rel_bucket(dist[u]) * 8 + g * 4 + myh] * LOG2E : -INFINITY; }
.LBB0_1589:
	s_andn2_saveexec_b64 s[82:83], s[82:83]
	v_max_i32_e32 v14, 0, v9
	s_or_b64 exec, exec, s[82:83]
	v_lshl_or_b32 v70, v14, 3, v104
	v_lshlrev_b32_e32 v70, 2, v70
	ds_read_b32 v70, v70 offset:63296
	s_waitcnt lgkmcnt(1)
	v_add_f32_e32 v8, v6, v7
	s_waitcnt lgkmcnt(0)
	v_fmac_f32_e32 v8, 0x3fb8aa3b, v70

; DI void snsa_unit(const Args& a, LAS unsigned char* lds, int s, int g) {
;     ...
;                 float ka = o1 ? p2 : p0, kb2 = o1 ? p3 : p1; const float sa = o1 ? p0 : p2, sb = o1 ? p1 : p3;
;                 ka += __shfl_xor(sa, 1); kb2 += __shfl_xor(sb, 1);
;                 float e = o2 ? kb2 : ka; const float f = o2 ? ka : kb2;
;                 e += __shfl_xor(f, 2); e += __shfl_xor(e, 4); e += __shfl_xor(e, 8);
;                 if (c16 < 4 && kk < nkeys) SC[myh * 1024 + kk] = valid[u] ? e + rbias[rel_bucket(dist[u]) * 8 + g * 4 + myh] * LOG2E : -INFINITY; }
.LBB0_1597:
	s_andn2_saveexec_b64 s[82:83], s[82:83]
	v_max_i32_e32 v9, 0, v10
	s_or_b64 exec, exec, s[82:83]
	v_lshl_or_b32 v70, v9, 3, v104
	v_lshlrev_b32_e32 v70, 2, v70
	ds_read_b32 v70, v70 offset:63296
	s_waitcnt lgkmcnt(1)
	v_add_f32_e32 v8, v6, v7
	s_waitcnt lgkmcnt(0)
	v_fmac_f32_e32 v8, 0x3fb8aa3b, v70

; DI void snsa_unit(const Args& a, LAS unsigned char* lds, int s, int g) {
;     ...
;                 float ka = o1 ? p2 : p0, kb2 = o1 ? p3 : p1; const float sa = o1 ? p0 : p2, sb = o1 ? p1 : p3;
;                 ka += __shfl_xor(sa, 1); kb2 += __shfl_xor(sb, 1);
;                 float e = o2 ? kb2 : ka; const float f = o2 ? ka : kb2;
;                 e += __shfl_xor(f, 2); e += __shfl_xor(e, 4); e += __shfl_xor(e, 8);
;                 if (c16 < 4 && kk < nkeys) SC[myh * 1024 + kk] = valid[u] ? e + rbias[rel_bucket(dist[u]) * 8 + g * 4 + myh] * LOG2E : -INFINITY; }
.LBB0_1605:
	s_andn2_saveexec_b64 s[82:83], s[82:83]
	v_max_i32_e32 v9, 0, v11
	s_or_b64 exec, exec, s[82:83]
	v_lshl_or_b32 v70, v9, 3, v104
	v_lshlrev_b32_e32 v70, 2, v70
	ds_read_b32 v70, v70 offset:63296
	s_waitcnt lgkmcnt(1)
	v_add_f32_e32 v8, v6, v7
	s_waitcnt lgkmcnt(0)
	v_fmac_f32_e32 v8, 0x3fb8aa3b, v70

; DI void snsa_unit(const Args& a, LAS unsigned char* lds, int s, int g) {
;     ...
;                 float ka = o1 ? p2 : p0, kb2 = o1 ? p3 : p1; const float sa = o1 ? p0 : p2, sb = o1 ? p1 : p3;
;                 ka += __shfl_xor(sa, 1); kb2 += __shfl_xor(sb, 1);
;                 float e = o2 ? kb2 : ka; const float f = o2 ? ka : kb2;
;                 e += __shfl_xor(f, 2); e += __shfl_xor(e, 4); e += __shfl_xor(e, 8);
;                 if (c16 < 4 && kk < nkeys) SC[myh * 1024 + kk] = valid[u] ? e + rbias[rel_bucket(dist[u]) * 8 + g * 4 + myh] * LOG2E : -INFINITY; }
.LBB0_1613:
	s_andn2_saveexec_b64 s[82:83], s[82:83]
	v_max_i32_e32 v9, 0, v12
	s_or_b64 exec, exec, s[82:83]
	v_lshl_or_b32 v70, v9, 3, v104
	v_lshlrev_b32_e32 v70, 2, v70
	ds_read_b32 v70, v70 offset:63296
	s_waitcnt lgkmcnt(1)
	v_add_f32_e32 v8, v6, v7
	s_waitcnt lgkmcnt(0)
	v_fmac_f32_e32 v8, 0x3fb8aa3b, v70
